# v13 + GQA tile body software-pipelined across key tiles (last two softmax/PV stages of a tile overlap the next tile's QK)
# baseline (speedup 1.0000x reference)
; template <int DQ, bool NA, int NQG>
; DI void attn_wg(const half_t* Qp, const half_t* Kp, const half_t* Vp, int q0, bool active, int seg0_start, int seg0_tiles,
;                 int seg1_start, int seg1_tiles, const float* rpb_h, int rq, char* smem, int tid, f16v (&O)[2][NQG]) {
;     ...
;         for (int ks = 0; ks < NKS; ++ks) {
;           const h8 kf = *(const h8*)(ksm + (st * 32) * KSTR + ks * 16);
; #pragma unroll
;           for (int qg = 0; qg < NQG; ++qg) S[qg] = __builtin_amdgcn_mfma_f32_32x32x16_f16(kf, qf[qg][ks], S[qg], 0, 0, 0);
;         }
;     ...
;         for (int qg = 0; qg < NQG; ++qg) {
;           h8 P[2];
;           float mx = S[qg][0];
; #pragma unroll
;           for (int i = 1; i < 16; ++i) mx = fmaxf(mx, S[qg][i]);
;           mx = fmaxf(mx, __shfl_xor(mx, 32));
;           if (__builtin_amdgcn_ballot_w64(mx > mrun[qg] + 8.f) != 0ull) {
;             const float mnew = fmaxf(mrun[qg], mx);
;             const float alpha = __builtin_amdgcn_exp2f(mrun[qg] - mnew);
;             lrun[qg] *= alpha;
; #pragma unroll
;             for (int dvt = 0; dvt < 2; ++dvt)
; #pragma unroll
;               for (int i = 0; i < 16; ++i) O[dvt][qg][i] *= alpha;
;             mrun[qg] = mnew;
;           }
;           const float mn = mrun[qg];
;           f2 rs2 = {0.f, 0.f};
;           const f2 mn2 = {mn, mn};
; #pragma unroll
;           for (int i = 0; i < 16; i += 2) {
;             const f2 s2 = {S[qg][i], S[qg][i + 1]};
;             const f2 d2 = s2 - mn2;
;             f2 p2;
;             p2.x = __builtin_amdgcn_exp2f(d2.x);
;             p2.y = __builtin_amdgcn_exp2f(d2.y);
;             if (NA) { p2.x = (s2.x <= -1e29f) ? 0.f : p2.x; p2.y = (s2.y <= -1e29f) ? 0.f : p2.y; }
;             rs2 += p2;
;             P[i >> 3][i & 7] = (half_t)p2.x;
;             P[i >> 3][(i & 7) + 1] = (half_t)p2.y;
;           }
;           lrun[qg] += rs2.x + rs2.y;
; #pragma unroll
;           for (int dvt = 0; dvt < 2; ++dvt) {
; #pragma unroll
;             for (int sx = 0; sx < 2; ++sx) {
;               const h8 va = __builtin_shufflevector(vf[dvt][sx][0], vf[dvt][sx][1], 0, 1, 2, 3, 4, 5, 6, 7);
;               O[dvt][qg] = __builtin_amdgcn_mfma_f32_32x32x16_f16(va, P[sx], O[dvt][qg], 0, 0, 0);
;             }
;           }
.LBB0_1917:
	v_cndmask_b32_e64 v66, 0, 1, s[14:15]
	v_cmp_ne_u32_e64 s[6:7], 1, v66
	s_andn2_b64 vcc, exec, s[14:15]
	s_cbranch_vccnz .LBB0_1924
	s_cmp_eq_u32 s22, 0
	s_cselect_b32 s68, 1, 0
	s_bitcmp1_b32 s22, 0
	s_cselect_b32 s22, 0x5800, 0
	v_add3_u32 v187, s22, v237, v156
	v_add3_u32 v189, s22, v237, v155
	v_add_u32_e32 v197, 0x4600, v189
	v_add_u32_e32 v189, 0x3400, v189
	s_cmp_lg_u32 s68, 0
	s_cbranch_scc1 .Lxtfirst_gqax
	ds_read_b128 v[198:201], v187 offset:0
	ds_read_b128 v[202:205], v187 offset:32
	ds_read_b128 v[206:209], v187 offset:64
	ds_read_b128 v[210:213], v187 offset:96
	v_max3_f32 v232, v82, v83, v84
	v_max3_f32 v233, v85, v86, v87
	v_max3_f32 v232, v232, v88, v89
	v_max3_f32 v233, v233, v90, v91
	v_mfma_f32_32x32x16_f16 v[2:17], v[138:141], v[214:217], v[2:17]
	v_max3_f32 v232, v232, v92, v93
	v_max3_f32 v233, v233, v94, v95
	v_max3_f32 v232, v232, v96, v97
	v_max_f32_e32 v232, v232, v233
	v_mov_b32_e32 v233, v232
	s_nop 1
	v_permlane32_swap_b32_e32 v233, v232
	v_max_f32_e32 v232, v232, v233
	v_mfma_f32_32x32x16_f16 v[18:33], v[146:149], v[214:217], v[18:33]
	v_add_f32_e32 v233, 0x41000000, v196
	v_cmp_gt_f32_e32 vcc, v232, v233
	s_cbranch_vccnz .Lresc_gqax_steady_3
.Lcont_gqax_steady_3:
	v_pk_add_f32 v[82:83], v[82:83], v[196:197] op_sel_hi:[1,0] neg_lo:[0,1] neg_hi:[0,1]
	v_pk_add_f32 v[84:85], v[84:85], v[196:197] op_sel_hi:[1,0] neg_lo:[0,1] neg_hi:[0,1]
	v_exp_f32_e32 v82, v82
	v_exp_f32_e32 v83, v83
	v_pk_add_f32 v[86:87], v[86:87], v[196:197] op_sel_hi:[1,0] neg_lo:[0,1] neg_hi:[0,1]
	v_mfma_f32_32x32x16_f16 v[2:17], v[142:145], v[218:221], v[2:17]
	v_exp_f32_e32 v84, v84
	v_exp_f32_e32 v85, v85
	v_pk_add_f32 v[88:89], v[88:89], v[196:197] op_sel_hi:[1,0] neg_lo:[0,1] neg_hi:[0,1]
	v_exp_f32_e32 v86, v86
	v_exp_f32_e32 v87, v87
	v_pk_add_f32 v[90:91], v[90:91], v[196:197] op_sel_hi:[1,0] neg_lo:[0,1] neg_hi:[0,1]
	v_exp_f32_e32 v88, v88
	v_mfma_f32_32x32x16_f16 v[18:33], v[150:153], v[218:221], v[18:33]
	v_exp_f32_e32 v89, v89
	v_pk_add_f32 v[92:93], v[92:93], v[196:197] op_sel_hi:[1,0] neg_lo:[0,1] neg_hi:[0,1]
	v_exp_f32_e32 v90, v90
	v_exp_f32_e32 v91, v91
	v_pk_add_f32 v[94:95], v[94:95], v[196:197] op_sel_hi:[1,0] neg_lo:[0,1] neg_hi:[0,1]
	s_waitcnt lgkmcnt(3)
	v_mfma_f32_32x32x16_f16 v[66:81], v[198:201], v[98:101], 0
	v_exp_f32_e32 v92, v92
	v_exp_f32_e32 v93, v93
	v_pk_add_f32 v[96:97], v[96:97], v[196:197] op_sel_hi:[1,0] neg_lo:[0,1] neg_hi:[0,1]
	s_waitcnt lgkmcnt(2)
	v_mfma_f32_32x32x16_f16 v[66:81], v[202:205], v[102:105], v[66:81]
	v_exp_f32_e32 v94, v94
	v_exp_f32_e32 v95, v95
	v_exp_f32_e32 v96, v96
	s_waitcnt lgkmcnt(1)
	v_mfma_f32_32x32x16_f16 v[66:81], v[206:209], v[106:109], v[66:81]
	v_exp_f32_e32 v97, v97
	v_cvt_pk_f16_f32 v214, v82, v83
	v_cvt_pk_f16_f32 v215, v84, v85
	s_waitcnt lgkmcnt(0)
	v_mfma_f32_32x32x16_f16 v[66:81], v[210:213], v[110:113], v[66:81]
	v_cvt_pk_f16_f32 v216, v86, v87
	v_cvt_pk_f16_f32 v217, v88, v89
	v_cvt_pk_f16_f32 v218, v90, v91
	v_cvt_pk_f16_f32 v219, v92, v93
	v_cvt_pk_f16_f32 v220, v94, v95
	v_cvt_pk_f16_f32 v221, v96, v97
	v_pk_add_f32 v[222:223], v[82:83], v[84:85]
	v_pk_add_f32 v[224:225], v[86:87], v[88:89]
	v_pk_add_f32 v[226:227], v[90:91], v[92:93]
	v_pk_add_f32 v[228:229], v[94:95], v[96:97]
	v_pk_add_f32 v[222:223], v[222:223], v[224:225]
	v_pk_add_f32 v[226:227], v[226:227], v[228:229]
	v_pk_add_f32 v[222:223], v[222:223], v[226:227]
	v_add_f32_e32 v222, v222, v223
	v_add_f32_e32 v1, v1, v222
	v_max3_f32 v232, v66, v67, v68
	v_max3_f32 v233, v69, v70, v71
	v_max3_f32 v232, v232, v72, v73
	v_max3_f32 v233, v233, v74, v75
	v_mfma_f32_32x32x16_f16 v[34:49], v[138:141], v[214:217], v[34:49]
	v_max3_f32 v232, v232, v76, v77
	v_max3_f32 v233, v233, v78, v79
	v_max3_f32 v232, v232, v80, v81
	v_max_f32_e32 v232, v232, v233
	v_mov_b32_e32 v233, v232
	s_nop 1
	v_permlane32_swap_b32_e32 v233, v232
	v_max_f32_e32 v232, v232, v233
	v_mfma_f32_32x32x16_f16 v[50:65], v[146:149], v[214:217], v[50:65]
	v_add_f32_e32 v233, 0x41000000, v194
	v_cmp_gt_f32_e32 vcc, v232, v233
	s_cbranch_vccnz .Lresc_gqax_steady_0
.Lcont_gqax_steady_0:
	v_pk_add_f32 v[66:67], v[66:67], v[194:195] op_sel_hi:[1,0] neg_lo:[0,1] neg_hi:[0,1]
	v_pk_add_f32 v[68:69], v[68:69], v[194:195] op_sel_hi:[1,0] neg_lo:[0,1] neg_hi:[0,1]
	v_exp_f32_e32 v66, v66
	v_exp_f32_e32 v67, v67
	v_pk_add_f32 v[70:71], v[70:71], v[194:195] op_sel_hi:[1,0] neg_lo:[0,1] neg_hi:[0,1]
	v_mfma_f32_32x32x16_f16 v[34:49], v[142:145], v[218:221], v[34:49]
	v_exp_f32_e32 v68, v68
	v_exp_f32_e32 v69, v69
	v_pk_add_f32 v[72:73], v[72:73], v[194:195] op_sel_hi:[1,0] neg_lo:[0,1] neg_hi:[0,1]
	v_exp_f32_e32 v70, v70
	v_exp_f32_e32 v71, v71
	v_pk_add_f32 v[74:75], v[74:75], v[194:195] op_sel_hi:[1,0] neg_lo:[0,1] neg_hi:[0,1]
	v_exp_f32_e32 v72, v72
	v_mfma_f32_32x32x16_f16 v[50:65], v[150:153], v[218:221], v[50:65]
	ds_read2_b64 v[138:141], v189 offset0:0 offset1:2
	ds_read2_b64 v[142:145], v189 offset0:4 offset1:6
	ds_read2_b64 v[146:149], v197 offset0:0 offset1:2
	ds_read2_b64 v[150:153], v197 offset0:4 offset1:6
	v_exp_f32_e32 v73, v73
	v_pk_add_f32 v[76:77], v[76:77], v[194:195] op_sel_hi:[1,0] neg_lo:[0,1] neg_hi:[0,1]
	v_exp_f32_e32 v74, v74
	v_exp_f32_e32 v75, v75
	v_pk_add_f32 v[78:79], v[78:79], v[194:195] op_sel_hi:[1,0] neg_lo:[0,1] neg_hi:[0,1]
	v_mfma_f32_32x32x16_f16 v[82:97], v[198:201], v[114:117], 0
	v_exp_f32_e32 v76, v76
	v_exp_f32_e32 v77, v77
	v_pk_add_f32 v[80:81], v[80:81], v[194:195] op_sel_hi:[1,0] neg_lo:[0,1] neg_hi:[0,1]
	v_mfma_f32_32x32x16_f16 v[82:97], v[202:205], v[118:121], v[82:97]
	v_exp_f32_e32 v78, v78
	v_exp_f32_e32 v79, v79
	v_exp_f32_e32 v80, v80
	v_mfma_f32_32x32x16_f16 v[82:97], v[206:209], v[122:125], v[82:97]
	v_exp_f32_e32 v81, v81
	v_cvt_pk_f16_f32 v214, v66, v67
	v_cvt_pk_f16_f32 v215, v68, v69
	v_mfma_f32_32x32x16_f16 v[82:97], v[210:213], v[126:129], v[82:97]
	v_cvt_pk_f16_f32 v216, v70, v71
	v_cvt_pk_f16_f32 v217, v72, v73
	v_cvt_pk_f16_f32 v218, v74, v75
	v_cvt_pk_f16_f32 v219, v76, v77
	v_cvt_pk_f16_f32 v220, v78, v79
	v_cvt_pk_f16_f32 v221, v80, v81
	v_pk_add_f32 v[222:223], v[66:67], v[68:69]
	v_pk_add_f32 v[224:225], v[70:71], v[72:73]
	v_pk_add_f32 v[226:227], v[74:75], v[76:77]
	v_pk_add_f32 v[228:229], v[78:79], v[80:81]
	v_pk_add_f32 v[222:223], v[222:223], v[224:225]
	v_pk_add_f32 v[226:227], v[226:227], v[228:229]
	v_pk_add_f32 v[222:223], v[222:223], v[226:227]
	v_add_f32_e32 v222, v222, v223
	v_add_f32_e32 v183, v183, v222
	ds_read_b128 v[198:201], v187 offset:4608
	ds_read_b128 v[202:205], v187 offset:4640
	ds_read_b128 v[206:209], v187 offset:4672
	ds_read_b128 v[210:213], v187 offset:4704
	v_max3_f32 v232, v82, v83, v84
	v_max3_f32 v233, v85, v86, v87
	v_max3_f32 v232, v232, v88, v89
	v_max3_f32 v233, v233, v90, v91
	s_waitcnt lgkmcnt(7)
; template <int DQ, bool NA, int NQG>
; DI void attn_wg(const half_t* Qp, const half_t* Kp, const half_t* Vp, int q0, bool active, int seg0_start, int seg0_tiles,
;                 int seg1_start, int seg1_tiles, const float* rpb_h, int rq, char* smem, int tid, f16v (&O)[2][NQG]) {
;     ...
;         for (int ks = 0; ks < NKS; ++ks) {
;           const h8 kf = *(const h8*)(ksm + (st * 32) * KSTR + ks * 16);
; #pragma unroll
;           for (int qg = 0; qg < NQG; ++qg) S[qg] = __builtin_amdgcn_mfma_f32_32x32x16_f16(kf, qf[qg][ks], S[qg], 0, 0, 0);
;         }
;     ...
;         for (int qg = 0; qg < NQG; ++qg) {
;           h8 P[2];
;           float mx = S[qg][0];
; #pragma unroll
;           for (int i = 1; i < 16; ++i) mx = fmaxf(mx, S[qg][i]);
;           mx = fmaxf(mx, __shfl_xor(mx, 32));
;           if (__builtin_amdgcn_ballot_w64(mx > mrun[qg] + 8.f) != 0ull) {
;             const float mnew = fmaxf(mrun[qg], mx);
;             const float alpha = __builtin_amdgcn_exp2f(mrun[qg] - mnew);
;             lrun[qg] *= alpha;
; #pragma unroll
;             for (int dvt = 0; dvt < 2; ++dvt)
; #pragma unroll
;               for (int i = 0; i < 16; ++i) O[dvt][qg][i] *= alpha;
;             mrun[qg] = mnew;
;           }
;           const float mn = mrun[qg];
;           f2 rs2 = {0.f, 0.f};
;           const f2 mn2 = {mn, mn};
; #pragma unroll
;           for (int i = 0; i < 16; i += 2) {
;             const f2 s2 = {S[qg][i], S[qg][i + 1]};
;             const f2 d2 = s2 - mn2;
;             f2 p2;
;             p2.x = __builtin_amdgcn_exp2f(d2.x);
;             p2.y = __builtin_amdgcn_exp2f(d2.y);
;             if (NA) { p2.x = (s2.x <= -1e29f) ? 0.f : p2.x; p2.y = (s2.y <= -1e29f) ? 0.f : p2.y; }
;             rs2 += p2;
;             P[i >> 3][i & 7] = (half_t)p2.x;
;             P[i >> 3][(i & 7) + 1] = (half_t)p2.y;
;           }
;           lrun[qg] += rs2.x + rs2.y;
; #pragma unroll
;           for (int dvt = 0; dvt < 2; ++dvt) {
; #pragma unroll
;             for (int sx = 0; sx < 2; ++sx) {
;               const h8 va = __builtin_shufflevector(vf[dvt][sx][0], vf[dvt][sx][1], 0, 1, 2, 3, 4, 5, 6, 7);
;               O[dvt][qg] = __builtin_amdgcn_mfma_f32_32x32x16_f16(va, P[sx], O[dvt][qg], 0, 0, 0);
;             }
;           }
	v_mfma_f32_32x32x16_f16 v[2:17], v[138:141], v[214:217], v[2:17]
	v_max3_f32 v232, v232, v92, v93
	v_max3_f32 v233, v233, v94, v95
	v_max3_f32 v232, v232, v96, v97
	v_max_f32_e32 v232, v232, v233
	v_mov_b32_e32 v233, v232
	s_nop 1
	v_permlane32_swap_b32_e32 v233, v232
	v_max_f32_e32 v232, v232, v233
	s_waitcnt lgkmcnt(5)
	v_mfma_f32_32x32x16_f16 v[18:33], v[146:149], v[214:217], v[18:33]
	v_add_f32_e32 v233, 0x41000000, v196
	v_cmp_gt_f32_e32 vcc, v232, v233
	s_cbranch_vccnz .Lresc_gqax_steady_1
.Lcont_gqax_steady_1:
	v_pk_add_f32 v[82:83], v[82:83], v[196:197] op_sel_hi:[1,0] neg_lo:[0,1] neg_hi:[0,1]
	v_pk_add_f32 v[84:85], v[84:85], v[196:197] op_sel_hi:[1,0] neg_lo:[0,1] neg_hi:[0,1]
	v_exp_f32_e32 v82, v82
	v_exp_f32_e32 v83, v83
	v_pk_add_f32 v[86:87], v[86:87], v[196:197] op_sel_hi:[1,0] neg_lo:[0,1] neg_hi:[0,1]
	v_mfma_f32_32x32x16_f16 v[2:17], v[142:145], v[218:221], v[2:17]
	v_exp_f32_e32 v84, v84
	v_exp_f32_e32 v85, v85
	v_pk_add_f32 v[88:89], v[88:89], v[196:197] op_sel_hi:[1,0] neg_lo:[0,1] neg_hi:[0,1]
	v_exp_f32_e32 v86, v86
	v_exp_f32_e32 v87, v87
	v_pk_add_f32 v[90:91], v[90:91], v[196:197] op_sel_hi:[1,0] neg_lo:[0,1] neg_hi:[0,1]
	v_exp_f32_e32 v88, v88
	s_waitcnt lgkmcnt(4)
	v_mfma_f32_32x32x16_f16 v[18:33], v[150:153], v[218:221], v[18:33]
	v_exp_f32_e32 v89, v89
	v_pk_add_f32 v[92:93], v[92:93], v[196:197] op_sel_hi:[1,0] neg_lo:[0,1] neg_hi:[0,1]
	v_exp_f32_e32 v90, v90
	v_exp_f32_e32 v91, v91
	v_pk_add_f32 v[94:95], v[94:95], v[196:197] op_sel_hi:[1,0] neg_lo:[0,1] neg_hi:[0,1]
	s_waitcnt lgkmcnt(3)
	v_mfma_f32_32x32x16_f16 v[66:81], v[198:201], v[98:101], 0
	v_exp_f32_e32 v92, v92
	v_exp_f32_e32 v93, v93
	v_pk_add_f32 v[96:97], v[96:97], v[196:197] op_sel_hi:[1,0] neg_lo:[0,1] neg_hi:[0,1]
	s_waitcnt lgkmcnt(2)
	v_mfma_f32_32x32x16_f16 v[66:81], v[202:205], v[102:105], v[66:81]
	v_exp_f32_e32 v94, v94
	v_exp_f32_e32 v95, v95
	v_exp_f32_e32 v96, v96
	s_waitcnt lgkmcnt(1)
	v_mfma_f32_32x32x16_f16 v[66:81], v[206:209], v[106:109], v[66:81]
	v_exp_f32_e32 v97, v97
	v_cvt_pk_f16_f32 v214, v82, v83
	v_cvt_pk_f16_f32 v215, v84, v85
	s_waitcnt lgkmcnt(0)
	v_mfma_f32_32x32x16_f16 v[66:81], v[210:213], v[110:113], v[66:81]
	v_cvt_pk_f16_f32 v216, v86, v87
	v_cvt_pk_f16_f32 v217, v88, v89
	v_cvt_pk_f16_f32 v218, v90, v91
	v_cvt_pk_f16_f32 v219, v92, v93
	v_cvt_pk_f16_f32 v220, v94, v95
	v_cvt_pk_f16_f32 v221, v96, v97
	v_pk_add_f32 v[222:223], v[82:83], v[84:85]
	v_pk_add_f32 v[224:225], v[86:87], v[88:89]
	v_pk_add_f32 v[226:227], v[90:91], v[92:93]
	v_pk_add_f32 v[228:229], v[94:95], v[96:97]
	v_pk_add_f32 v[222:223], v[222:223], v[224:225]
	v_pk_add_f32 v[226:227], v[226:227], v[228:229]
	v_pk_add_f32 v[222:223], v[222:223], v[226:227]
	v_add_f32_e32 v222, v222, v223
	v_add_f32_e32 v1, v1, v222
	v_max3_f32 v232, v66, v67, v68
	v_max3_f32 v233, v69, v70, v71
	v_max3_f32 v232, v232, v72, v73
	v_max3_f32 v233, v233, v74, v75
	v_mfma_f32_32x32x16_f16 v[34:49], v[138:141], v[214:217], v[34:49]
	v_max3_f32 v232, v232, v76, v77
	v_max3_f32 v233, v233, v78, v79
	v_max3_f32 v232, v232, v80, v81
	v_max_f32_e32 v232, v232, v233
	v_mov_b32_e32 v233, v232
	s_nop 1
	v_permlane32_swap_b32_e32 v233, v232
	v_max_f32_e32 v232, v232, v233
	v_mfma_f32_32x32x16_f16 v[50:65], v[146:149], v[214:217], v[50:65]
	v_add_f32_e32 v233, 0x41000000, v194
	v_cmp_gt_f32_e32 vcc, v232, v233
	s_cbranch_vccnz .Lresc_gqax_steady_2
.Lcont_gqax_steady_2:
	v_pk_add_f32 v[66:67], v[66:67], v[194:195] op_sel_hi:[1,0] neg_lo:[0,1] neg_hi:[0,1]
	v_pk_add_f32 v[68:69], v[68:69], v[194:195] op_sel_hi:[1,0] neg_lo:[0,1] neg_hi:[0,1]
	v_exp_f32_e32 v66, v66
	v_exp_f32_e32 v67, v67
	v_pk_add_f32 v[70:71], v[70:71], v[194:195] op_sel_hi:[1,0] neg_lo:[0,1] neg_hi:[0,1]
	v_mfma_f32_32x32x16_f16 v[34:49], v[142:145], v[218:221], v[34:49]
	v_exp_f32_e32 v68, v68
	v_exp_f32_e32 v69, v69
	v_pk_add_f32 v[72:73], v[72:73], v[194:195] op_sel_hi:[1,0] neg_lo:[0,1] neg_hi:[0,1]
	v_exp_f32_e32 v70, v70
	v_exp_f32_e32 v71, v71
	v_pk_add_f32 v[74:75], v[74:75], v[194:195] op_sel_hi:[1,0] neg_lo:[0,1] neg_hi:[0,1]
	v_exp_f32_e32 v72, v72
	v_mfma_f32_32x32x16_f16 v[50:65], v[150:153], v[218:221], v[50:65]
	ds_read2_b64 v[138:141], v189 offset0:8 offset1:10
	ds_read2_b64 v[142:145], v189 offset0:12 offset1:14
	ds_read2_b64 v[146:149], v197 offset0:8 offset1:10
	ds_read2_b64 v[150:153], v197 offset0:12 offset1:14
	v_exp_f32_e32 v73, v73
	v_pk_add_f32 v[76:77], v[76:77], v[194:195] op_sel_hi:[1,0] neg_lo:[0,1] neg_hi:[0,1]
	v_exp_f32_e32 v74, v74
	v_exp_f32_e32 v75, v75
	v_pk_add_f32 v[78:79], v[78:79], v[194:195] op_sel_hi:[1,0] neg_lo:[0,1] neg_hi:[0,1]
	v_mfma_f32_32x32x16_f16 v[82:97], v[198:201], v[114:117], 0
	v_exp_f32_e32 v76, v76
	v_exp_f32_e32 v77, v77
	v_pk_add_f32 v[80:81], v[80:81], v[194:195] op_sel_hi:[1,0] neg_lo:[0,1] neg_hi:[0,1]
	v_mfma_f32_32x32x16_f16 v[82:97], v[202:205], v[118:121], v[82:97]
	v_exp_f32_e32 v78, v78
	v_exp_f32_e32 v79, v79
	v_exp_f32_e32 v80, v80
	v_mfma_f32_32x32x16_f16 v[82:97], v[206:209], v[122:125], v[82:97]
	v_exp_f32_e32 v81, v81
	v_cvt_pk_f16_f32 v214, v66, v67
	v_cvt_pk_f16_f32 v215, v68, v69
	v_mfma_f32_32x32x16_f16 v[82:97], v[210:213], v[126:129], v[82:97]
	v_cvt_pk_f16_f32 v216, v70, v71
	v_cvt_pk_f16_f32 v217, v72, v73
	v_cvt_pk_f16_f32 v218, v74, v75
	v_cvt_pk_f16_f32 v219, v76, v77
	v_cvt_pk_f16_f32 v220, v78, v79
	v_cvt_pk_f16_f32 v221, v80, v81
	v_pk_add_f32 v[222:223], v[66:67], v[68:69]
	v_pk_add_f32 v[224:225], v[70:71], v[72:73]
	v_pk_add_f32 v[226:227], v[74:75], v[76:77]
	v_pk_add_f32 v[228:229], v[78:79], v[80:81]
	v_pk_add_f32 v[222:223], v[222:223], v[224:225]
	v_pk_add_f32 v[226:227], v[226:227], v[228:229]
	v_pk_add_f32 v[222:223], v[222:223], v[226:227]
	v_add_f32_e32 v222, v222, v223
	v_add_f32_e32 v183, v183, v222
	s_branch .Lend_gqax_steady
; template <int DQ, bool NA, int NQG>
; DI void attn_wg(const half_t* Qp, const half_t* Kp, const half_t* Vp, int q0, bool active, int seg0_start, int seg0_tiles,
;                 int seg1_start, int seg1_tiles, const float* rpb_h, int rq, char* smem, int tid, f16v (&O)[2][NQG]) {
;     ...
;         for (int ks = 0; ks < NKS; ++ks) {
;           const h8 kf = *(const h8*)(ksm + (st * 32) * KSTR + ks * 16);
; #pragma unroll
;           for (int qg = 0; qg < NQG; ++qg) S[qg] = __builtin_amdgcn_mfma_f32_32x32x16_f16(kf, qf[qg][ks], S[qg], 0, 0, 0);
;         }
;     ...
;         for (int qg = 0; qg < NQG; ++qg) {
;           h8 P[2];
;           float mx = S[qg][0];
; #pragma unroll
;           for (int i = 1; i < 16; ++i) mx = fmaxf(mx, S[qg][i]);
;           mx = fmaxf(mx, __shfl_xor(mx, 32));
;           if (__builtin_amdgcn_ballot_w64(mx > mrun[qg] + 8.f) != 0ull) {
;             const float mnew = fmaxf(mrun[qg], mx);
;             const float alpha = __builtin_amdgcn_exp2f(mrun[qg] - mnew);
;             lrun[qg] *= alpha;
; #pragma unroll
;             for (int dvt = 0; dvt < 2; ++dvt)
; #pragma unroll
;               for (int i = 0; i < 16; ++i) O[dvt][qg][i] *= alpha;
;             mrun[qg] = mnew;
;           }
;           const float mn = mrun[qg];
;           f2 rs2 = {0.f, 0.f};
;           const f2 mn2 = {mn, mn};
; #pragma unroll
;           for (int i = 0; i < 16; i += 2) {
;             const f2 s2 = {S[qg][i], S[qg][i + 1]};
;             const f2 d2 = s2 - mn2;
;             f2 p2;
;             p2.x = __builtin_amdgcn_exp2f(d2.x);
;             p2.y = __builtin_amdgcn_exp2f(d2.y);
;             if (NA) { p2.x = (s2.x <= -1e29f) ? 0.f : p2.x; p2.y = (s2.y <= -1e29f) ? 0.f : p2.y; }
;             rs2 += p2;
;             P[i >> 3][i & 7] = (half_t)p2.x;
;             P[i >> 3][(i & 7) + 1] = (half_t)p2.y;
;           }
;           lrun[qg] += rs2.x + rs2.y;
.Lxtfirst_gqax:
	ds_read_b128 v[198:201], v187 offset:0
	ds_read_b128 v[202:205], v187 offset:32
	ds_read_b128 v[206:209], v187 offset:64
	ds_read_b128 v[210:213], v187 offset:96
	ds_read2_b64 v[138:141], v189 offset0:0 offset1:2
	ds_read2_b64 v[142:145], v189 offset0:4 offset1:6
	ds_read2_b64 v[146:149], v197 offset0:0 offset1:2
	ds_read2_b64 v[150:153], v197 offset0:4 offset1:6
	s_waitcnt lgkmcnt(7)
	v_mfma_f32_32x32x16_f16 v[66:81], v[198:201], v[98:101], 0
	s_waitcnt lgkmcnt(6)
	v_mfma_f32_32x32x16_f16 v[66:81], v[202:205], v[102:105], v[66:81]
	s_waitcnt lgkmcnt(5)
	v_mfma_f32_32x32x16_f16 v[66:81], v[206:209], v[106:109], v[66:81]
	s_waitcnt lgkmcnt(4)
	v_mfma_f32_32x32x16_f16 v[66:81], v[210:213], v[110:113], v[66:81]
	s_nop 11
	v_max3_f32 v232, v66, v67, v68
	v_max3_f32 v233, v69, v70, v71
	v_max3_f32 v232, v232, v72, v73
	v_max3_f32 v233, v233, v74, v75
	v_max3_f32 v232, v232, v76, v77
	v_max3_f32 v233, v233, v78, v79
	v_max3_f32 v232, v232, v80, v81
	v_mfma_f32_32x32x16_f16 v[82:97], v[198:201], v[114:117], 0
	v_max_f32_e32 v232, v232, v233
	v_mov_b32_e32 v233, v232
	s_nop 1
	v_permlane32_swap_b32_e32 v233, v232
	v_max_f32_e32 v232, v232, v233
	v_add_f32_e32 v233, 0x41000000, v194
	v_cmp_gt_f32_e32 vcc, v232, v233
	s_cbranch_vccnz .Lresc_gqax_first_0
.Lcont_gqax_first_0:
	v_pk_add_f32 v[66:67], v[66:67], v[194:195] op_sel_hi:[1,0] neg_lo:[0,1] neg_hi:[0,1]
	v_pk_add_f32 v[68:69], v[68:69], v[194:195] op_sel_hi:[1,0] neg_lo:[0,1] neg_hi:[0,1]
	v_exp_f32_e32 v66, v66
	v_mfma_f32_32x32x16_f16 v[82:97], v[202:205], v[118:121], v[82:97]
	v_exp_f32_e32 v67, v67
	v_pk_add_f32 v[70:71], v[70:71], v[194:195] op_sel_hi:[1,0] neg_lo:[0,1] neg_hi:[0,1]
	v_exp_f32_e32 v68, v68
	v_exp_f32_e32 v69, v69
	v_pk_add_f32 v[72:73], v[72:73], v[194:195] op_sel_hi:[1,0] neg_lo:[0,1] neg_hi:[0,1]
	v_exp_f32_e32 v70, v70
	v_exp_f32_e32 v71, v71
	v_pk_add_f32 v[74:75], v[74:75], v[194:195] op_sel_hi:[1,0] neg_lo:[0,1] neg_hi:[0,1]
	v_exp_f32_e32 v72, v72
	v_exp_f32_e32 v73, v73
	v_mfma_f32_32x32x16_f16 v[82:97], v[206:209], v[122:125], v[82:97]
	v_pk_add_f32 v[76:77], v[76:77], v[194:195] op_sel_hi:[1,0] neg_lo:[0,1] neg_hi:[0,1]
	v_exp_f32_e32 v74, v74
	v_exp_f32_e32 v75, v75
	v_pk_add_f32 v[78:79], v[78:79], v[194:195] op_sel_hi:[1,0] neg_lo:[0,1] neg_hi:[0,1]
	v_exp_f32_e32 v76, v76
	v_exp_f32_e32 v77, v77
	v_pk_add_f32 v[80:81], v[80:81], v[194:195] op_sel_hi:[1,0] neg_lo:[0,1] neg_hi:[0,1]
	v_exp_f32_e32 v78, v78
	v_exp_f32_e32 v79, v79
	v_exp_f32_e32 v80, v80
	v_mfma_f32_32x32x16_f16 v[82:97], v[210:213], v[126:129], v[82:97]
	v_exp_f32_e32 v81, v81
	v_cvt_pk_f16_f32 v214, v66, v67
	v_cvt_pk_f16_f32 v215, v68, v69
	v_cvt_pk_f16_f32 v216, v70, v71
	v_cvt_pk_f16_f32 v217, v72, v73
	v_cvt_pk_f16_f32 v218, v74, v75
	v_cvt_pk_f16_f32 v219, v76, v77
	v_cvt_pk_f16_f32 v220, v78, v79
	v_cvt_pk_f16_f32 v221, v80, v81
	v_pk_add_f32 v[222:223], v[66:67], v[68:69]
	v_pk_add_f32 v[224:225], v[70:71], v[72:73]
	v_pk_add_f32 v[226:227], v[74:75], v[76:77]
	v_pk_add_f32 v[228:229], v[78:79], v[80:81]
	v_pk_add_f32 v[222:223], v[222:223], v[224:225]
	v_pk_add_f32 v[226:227], v[226:227], v[228:229]
	v_pk_add_f32 v[222:223], v[222:223], v[226:227]
	v_add_f32_e32 v222, v222, v223
	v_add_f32_e32 v183, v183, v222
	ds_read_b128 v[198:201], v187 offset:4608
	ds_read_b128 v[202:205], v187 offset:4640
	ds_read_b128 v[206:209], v187 offset:4672
	ds_read_b128 v[210:213], v187 offset:4704
	v_max3_f32 v232, v82, v83, v84
	v_max3_f32 v233, v85, v86, v87
	v_max3_f32 v232, v232, v88, v89
	v_max3_f32 v233, v233, v90, v91
	s_waitcnt lgkmcnt(7)
	v_mfma_f32_32x32x16_f16 v[2:17], v[138:141], v[214:217], v[2:17]
	v_max3_f32 v232, v232, v92, v93
	v_max3_f32 v233, v233, v94, v95
	v_max3_f32 v232, v232, v96, v97
	v_max_f32_e32 v232, v232, v233
	v_mov_b32_e32 v233, v232
	s_nop 1
	v_permlane32_swap_b32_e32 v233, v232
	v_max_f32_e32 v232, v232, v233
	s_waitcnt lgkmcnt(5)
	v_mfma_f32_32x32x16_f16 v[18:33], v[146:149], v[214:217], v[18:33]
	v_add_f32_e32 v233, 0x41000000, v196
	v_cmp_gt_f32_e32 vcc, v232, v233
	s_cbranch_vccnz .Lresc_gqax_first_1

; template <int DQ, bool NA, int NQG>
; DI void attn_wg(const half_t* Qp, const half_t* Kp, const half_t* Vp, int q0, bool active, int seg0_start, int seg0_tiles,
;                 int seg1_start, int seg1_tiles, const float* rpb_h, int rq, char* smem, int tid, f16v (&O)[2][NQG]) {
;     ...
;     if (more) {
;       char* nb = smem + ((it + 1) & 1) * ATT_STAGE;
;       if (kc0 < KCH) *(uint4*)((half_t*)nb + ks0) = kreg0;
;       if (DQ == 96 && kc1 < KCH) *(uint4*)((half_t*)nb + ks1) = kreg1;
;       *(uint4*)((half_t*)(nb + ATT_VOFF) + vs0) = vreg;
;     }
.Lend_gqax_first:
.Lend_gqax_steady:
.Lend_gqax:
.LBB0_1924:
	s_andn2_b64 vcc, exec, s[8:9]
	s_cbranch_vccnz .LBB0_1928
	s_bitcmp1_b32 s46, 0
	s_cselect_b32 s22, 0x5800, 0
	s_and_saveexec_b64 s[8:9], s[2:3]
	s_cbranch_execz .LBB0_1927
	v_lshl_add_u32 v66, v181, 1, s22
	s_waitcnt vmcnt(1)
	ds_write_b128 v66, v[130:133]

; template <int DQ, bool NA, int NQG>
; DI void attn_wg(const half_t* Qp, const half_t* Kp, const half_t* Vp, int q0, bool active, int seg0_start, int seg0_tiles,
;                 int seg1_start, int seg1_tiles, const float* rpb_h, int rq, char* smem, int tid, f16v (&O)[2][NQG]) {
;     ...
;         for (int qg = 0; qg < NQG; ++qg) {
;           h8 P[2];
;           float mx = S[qg][0];
; #pragma unroll
;           for (int i = 1; i < 16; ++i) mx = fmaxf(mx, S[qg][i]);
;           mx = fmaxf(mx, __shfl_xor(mx, 32));
;           if (__builtin_amdgcn_ballot_w64(mx > mrun[qg] + 8.f) != 0ull) {
;             const float mnew = fmaxf(mrun[qg], mx);
;             const float alpha = __builtin_amdgcn_exp2f(mrun[qg] - mnew);
;             lrun[qg] *= alpha;
; #pragma unroll
;             for (int dvt = 0; dvt < 2; ++dvt)
; #pragma unroll
;               for (int i = 0; i < 16; ++i) O[dvt][qg][i] *= alpha;
;             mrun[qg] = mnew;
;           }
;           const float mn = mrun[qg];
;           f2 rs2 = {0.f, 0.f};
;           const f2 mn2 = {mn, mn};
; #pragma unroll
;           for (int i = 0; i < 16; i += 2) {
;             const f2 s2 = {S[qg][i], S[qg][i + 1]};
;             const f2 d2 = s2 - mn2;
;             f2 p2;
;             p2.x = __builtin_amdgcn_exp2f(d2.x);
;             p2.y = __builtin_amdgcn_exp2f(d2.y);
;             if (NA) { p2.x = (s2.x <= -1e29f) ? 0.f : p2.x; p2.y = (s2.y <= -1e29f) ? 0.f : p2.y; }
;             rs2 += p2;
;             P[i >> 3][i & 7] = (half_t)p2.x;
;             P[i >> 3][(i & 7) + 1] = (half_t)p2.y;
;           }
;           lrun[qg] += rs2.x + rs2.y;
; #pragma unroll
;           for (int dvt = 0; dvt < 2; ++dvt) {
; #pragma unroll
;             for (int sx = 0; sx < 2; ++sx) {
;               const h8 va = __builtin_shufflevector(vf[dvt][sx][0], vf[dvt][sx][1], 0, 1, 2, 3, 4, 5, 6, 7);
;               O[dvt][qg] = __builtin_amdgcn_mfma_f32_32x32x16_f16(va, P[sx], O[dvt][qg], 0, 0, 0);
;             }
;           }
.LBB0_1930:
	s_andn2_b64 vcc, exec, s[14:15]
	s_cbranch_vccnz .Lend_gqax_epi
	v_max3_f32 v232, v82, v83, v84
	v_max3_f32 v233, v85, v86, v87
	v_max3_f32 v232, v232, v88, v89
	v_max3_f32 v233, v233, v90, v91
	v_mfma_f32_32x32x16_f16 v[2:17], v[138:141], v[214:217], v[2:17]
	v_max3_f32 v232, v232, v92, v93
	v_max3_f32 v233, v233, v94, v95
	v_max3_f32 v232, v232, v96, v97
	v_max_f32_e32 v232, v232, v233
	v_mov_b32_e32 v233, v232
	s_nop 1
	v_permlane32_swap_b32_e32 v233, v232
	v_max_f32_e32 v232, v232, v233
	v_mfma_f32_32x32x16_f16 v[18:33], v[146:149], v[214:217], v[18:33]
	v_add_f32_e32 v233, 0x41000000, v196
	v_cmp_gt_f32_e32 vcc, v232, v233
	s_cbranch_vccnz .Lresc_gqax_epi_3
.Lcont_gqax_epi_3:
	v_pk_add_f32 v[82:83], v[82:83], v[196:197] op_sel_hi:[1,0] neg_lo:[0,1] neg_hi:[0,1]
	v_pk_add_f32 v[84:85], v[84:85], v[196:197] op_sel_hi:[1,0] neg_lo:[0,1] neg_hi:[0,1]
	v_exp_f32_e32 v82, v82
	v_exp_f32_e32 v83, v83
	v_pk_add_f32 v[86:87], v[86:87], v[196:197] op_sel_hi:[1,0] neg_lo:[0,1] neg_hi:[0,1]
	v_mfma_f32_32x32x16_f16 v[2:17], v[142:145], v[218:221], v[2:17]
	v_exp_f32_e32 v84, v84
	v_exp_f32_e32 v85, v85
	v_pk_add_f32 v[88:89], v[88:89], v[196:197] op_sel_hi:[1,0] neg_lo:[0,1] neg_hi:[0,1]
	v_exp_f32_e32 v86, v86
	v_exp_f32_e32 v87, v87
	v_pk_add_f32 v[90:91], v[90:91], v[196:197] op_sel_hi:[1,0] neg_lo:[0,1] neg_hi:[0,1]
	v_exp_f32_e32 v88, v88
	v_mfma_f32_32x32x16_f16 v[18:33], v[150:153], v[218:221], v[18:33]
	v_exp_f32_e32 v89, v89
	v_pk_add_f32 v[92:93], v[92:93], v[196:197] op_sel_hi:[1,0] neg_lo:[0,1] neg_hi:[0,1]
	v_exp_f32_e32 v90, v90
	v_exp_f32_e32 v91, v91
	v_pk_add_f32 v[94:95], v[94:95], v[196:197] op_sel_hi:[1,0] neg_lo:[0,1] neg_hi:[0,1]
	v_exp_f32_e32 v92, v92
	v_exp_f32_e32 v93, v93
	v_pk_add_f32 v[96:97], v[96:97], v[196:197] op_sel_hi:[1,0] neg_lo:[0,1] neg_hi:[0,1]
	v_exp_f32_e32 v94, v94
	v_exp_f32_e32 v95, v95
	v_exp_f32_e32 v96, v96
	v_exp_f32_e32 v97, v97
	v_cvt_pk_f16_f32 v214, v82, v83
	v_cvt_pk_f16_f32 v215, v84, v85
	v_cvt_pk_f16_f32 v216, v86, v87
	v_cvt_pk_f16_f32 v217, v88, v89
	v_cvt_pk_f16_f32 v218, v90, v91
	v_cvt_pk_f16_f32 v219, v92, v93
	v_cvt_pk_f16_f32 v220, v94, v95
	v_cvt_pk_f16_f32 v221, v96, v97
	v_pk_add_f32 v[222:223], v[82:83], v[84:85]
	v_pk_add_f32 v[224:225], v[86:87], v[88:89]
	v_pk_add_f32 v[226:227], v[90:91], v[92:93]
	v_pk_add_f32 v[228:229], v[94:95], v[96:97]
	v_pk_add_f32 v[222:223], v[222:223], v[224:225]
	v_pk_add_f32 v[226:227], v[226:227], v[228:229]
	v_pk_add_f32 v[222:223], v[222:223], v[226:227]
	v_add_f32_e32 v222, v222, v223
	v_add_f32_e32 v1, v1, v222
	v_mfma_f32_32x32x16_f16 v[34:49], v[138:141], v[214:217], v[34:49]
	v_mfma_f32_32x32x16_f16 v[50:65], v[146:149], v[214:217], v[50:65]
	v_mfma_f32_32x32x16_f16 v[34:49], v[142:145], v[218:221], v[34:49]
	v_mfma_f32_32x32x16_f16 v[50:65], v[150:153], v[218:221], v[50:65]
	s_branch .Lend_gqax_epi
